# GEMM tile headers: accumulator zeroing with v_pk_mov_b32 pairs (half the VALU issue slots)
# speedup vs baseline: 1.0011x; 1.0011x over previous
; template <class Epi, class Sched, bool ALIGN_EPI = false, bool SP2 = false>
; __device__ __forceinline__ void gemm_phase(PG8_LAS unsigned char* lds, const Gemm g, const Sched& S, const Epi& E) {
;     ...
;         const bool has_next = S.next(ui + 1, nxt);
;         const char* nA = has_next ? (const char*)g.A + (size_t)nxt.pm * tstep : cA; const char* nB = has_next ? (const char*)g.Bt + (size_t)nxt.pn * tstep : cB;
;     ...
; #pragma unroll
;         for (int a = 0; a < 2; ++a)
; #pragma unroll
;             for (int b = 0; b < 2; ++b)
; #pragma unroll
;                 for (int m = 0; m < 4; ++m)
; #pragma unroll
;                     for (int n = 0; n < 2; ++n) acc[a][b][m][n] = (f32x4){0.f, 0.f, 0.f, 0.f};
.LBB0_216:
	s_ashr_i32 s41, s40, 31
	s_lshl_b64 s[42:43], s[40:41], 20
	s_add_u32 s42, s62, s42
	s_addc_u32 s43, s63, s43
	s_and_b64 s[44:45], s[6:7], exec
	s_cselect_b32 s9, s43, s11
	s_cselect_b32 s15, s42, s10
	s_ashr_i32 s39, s38, 31
	s_lshl_b64 s[44:45], s[38:39], 20
	s_add_u32 s44, s64, s44
	s_addc_u32 s45, s65, s45
	s_and_b64 s[46:47], s[6:7], exec
	s_cselect_b32 s33, s45, s13
	s_cselect_b32 s39, s44, s12
	s_add_u32 s10, s10, 0x80080
	s_addc_u32 s11, s11, 0
	s_add_u32 s41, s12, 0x100
	v_mov_b32_e32 v0, 0
	s_addc_u32 s48, s13, 0
	s_mov_b32 s49, -2
	s_waitcnt lgkmcnt(0)
	v_mov_b32_e32 v1, v0
	v_pk_mov_b32 v[2:3], v[0:1], v[0:1]
	v_pk_mov_b32 v[4:5], v[0:1], v[0:1]
	v_pk_mov_b32 v[6:7], v[0:1], v[0:1]
	v_pk_mov_b32 v[16:17], v[0:1], v[0:1]
	v_pk_mov_b32 v[18:19], v[0:1], v[0:1]
	v_pk_mov_b32 v[20:21], v[0:1], v[0:1]
	v_pk_mov_b32 v[22:23], v[0:1], v[0:1]
	v_pk_mov_b32 v[32:33], v[0:1], v[0:1]
	v_pk_mov_b32 v[34:35], v[0:1], v[0:1]
	v_pk_mov_b32 v[36:37], v[0:1], v[0:1]
	v_pk_mov_b32 v[38:39], v[0:1], v[0:1]
	v_pk_mov_b32 v[48:49], v[0:1], v[0:1]
	v_pk_mov_b32 v[50:51], v[0:1], v[0:1]
	v_pk_mov_b32 v[52:53], v[0:1], v[0:1]
	v_pk_mov_b32 v[54:55], v[0:1], v[0:1]
	v_pk_mov_b32 v[8:9], v[0:1], v[0:1]
	v_pk_mov_b32 v[10:11], v[0:1], v[0:1]
	v_pk_mov_b32 v[12:13], v[0:1], v[0:1]
	v_pk_mov_b32 v[14:15], v[0:1], v[0:1]
	v_pk_mov_b32 v[24:25], v[0:1], v[0:1]
	v_pk_mov_b32 v[26:27], v[0:1], v[0:1]
	v_pk_mov_b32 v[28:29], v[0:1], v[0:1]
	v_pk_mov_b32 v[30:31], v[0:1], v[0:1]
	v_pk_mov_b32 v[40:41], v[0:1], v[0:1]
	v_pk_mov_b32 v[42:43], v[0:1], v[0:1]
	v_pk_mov_b32 v[44:45], v[0:1], v[0:1]
	v_pk_mov_b32 v[46:47], v[0:1], v[0:1]
	v_pk_mov_b32 v[56:57], v[0:1], v[0:1]
	v_pk_mov_b32 v[58:59], v[0:1], v[0:1]
	v_pk_mov_b32 v[60:61], v[0:1], v[0:1]
	v_pk_mov_b32 v[62:63], v[0:1], v[0:1]
	v_pk_mov_b32 v[64:65], v[0:1], v[0:1]
	v_pk_mov_b32 v[66:67], v[0:1], v[0:1]
	v_pk_mov_b32 v[68:69], v[0:1], v[0:1]
	v_pk_mov_b32 v[70:71], v[0:1], v[0:1]
	v_pk_mov_b32 v[80:81], v[0:1], v[0:1]
	v_pk_mov_b32 v[82:83], v[0:1], v[0:1]
	v_pk_mov_b32 v[84:85], v[0:1], v[0:1]
	v_pk_mov_b32 v[86:87], v[0:1], v[0:1]
	v_pk_mov_b32 v[96:97], v[0:1], v[0:1]
	v_pk_mov_b32 v[98:99], v[0:1], v[0:1]
	v_pk_mov_b32 v[100:101], v[0:1], v[0:1]
	v_pk_mov_b32 v[102:103], v[0:1], v[0:1]
	v_pk_mov_b32 v[112:113], v[0:1], v[0:1]
	v_pk_mov_b32 v[114:115], v[0:1], v[0:1]
	v_pk_mov_b32 v[116:117], v[0:1], v[0:1]
	v_pk_mov_b32 v[118:119], v[0:1], v[0:1]
	v_pk_mov_b32 v[72:73], v[0:1], v[0:1]
	v_pk_mov_b32 v[74:75], v[0:1], v[0:1]
	v_pk_mov_b32 v[76:77], v[0:1], v[0:1]
	v_pk_mov_b32 v[78:79], v[0:1], v[0:1]
	v_pk_mov_b32 v[88:89], v[0:1], v[0:1]
	v_pk_mov_b32 v[90:91], v[0:1], v[0:1]
	v_pk_mov_b32 v[92:93], v[0:1], v[0:1]
	v_pk_mov_b32 v[94:95], v[0:1], v[0:1]
	v_pk_mov_b32 v[104:105], v[0:1], v[0:1]
	v_pk_mov_b32 v[106:107], v[0:1], v[0:1]
	v_pk_mov_b32 v[108:109], v[0:1], v[0:1]
	v_pk_mov_b32 v[110:111], v[0:1], v[0:1]
	v_pk_mov_b32 v[120:121], v[0:1], v[0:1]
	v_pk_mov_b32 v[122:123], v[0:1], v[0:1]
	v_pk_mov_b32 v[124:125], v[0:1], v[0:1]
	v_pk_mov_b32 v[126:127], v[0:1], v[0:1]

; template <class Epi, class Sched, bool ALIGN_EPI = false, bool SP2 = false>
; __device__ __forceinline__ void gemm_phase(PG8_LAS unsigned char* lds, const Gemm g, const Sched& S, const Epi& E) {
;     ...
;         const bool has_next = S.next(ui + 1, nxt);
;         const char* nA = has_next ? (const char*)g.A + (size_t)nxt.pm * tstep : cA; const char* nB = has_next ? (const char*)g.Bt + (size_t)nxt.pn * tstep : cB;
;     ...
; #pragma unroll
;         for (int a = 0; a < 2; ++a)
; #pragma unroll
;             for (int b = 0; b < 2; ++b)
; #pragma unroll
;                 for (int m = 0; m < 4; ++m)
; #pragma unroll
;                     for (int n = 0; n < 2; ++n) acc[a][b][m][n] = (f32x4){0.f, 0.f, 0.f, 0.f};
.LBB0_566:
	s_ashr_i32 s25, s24, 31
	s_lshl_b64 s[26:27], s[24:25], 18
	s_add_u32 s26, s40, s26
	s_addc_u32 s27, s41, s27
	s_and_b64 s[28:29], s[4:5], exec
	s_cselect_b32 s7, s27, s35
	s_cselect_b32 s25, s26, s34
	s_ashr_i32 s23, s22, 31
	s_lshl_b64 s[28:29], s[22:23], 18
	s_add_u32 s28, s42, s28
	s_addc_u32 s29, s43, s29
	s_and_b64 s[38:39], s[4:5], exec
	s_cselect_b32 s23, s29, s37
	s_cselect_b32 s31, s28, s36
	s_add_u32 s34, s34, 0x20080
	s_addc_u32 s35, s35, 0
	s_add_u32 s33, s36, 0x100
	v_mov_b32_e32 v0, 0
	s_addc_u32 s65, s37, 0
	s_mov_b32 s66, -2
	v_mov_b32_e32 v1, v0
	v_pk_mov_b32 v[2:3], v[0:1], v[0:1]
	v_pk_mov_b32 v[4:5], v[0:1], v[0:1]
	v_pk_mov_b32 v[6:7], v[0:1], v[0:1]
	v_pk_mov_b32 v[16:17], v[0:1], v[0:1]
	v_pk_mov_b32 v[18:19], v[0:1], v[0:1]
	v_pk_mov_b32 v[20:21], v[0:1], v[0:1]
	v_pk_mov_b32 v[22:23], v[0:1], v[0:1]
	v_pk_mov_b32 v[32:33], v[0:1], v[0:1]
	v_pk_mov_b32 v[34:35], v[0:1], v[0:1]
	v_pk_mov_b32 v[36:37], v[0:1], v[0:1]
	v_pk_mov_b32 v[38:39], v[0:1], v[0:1]
	v_pk_mov_b32 v[48:49], v[0:1], v[0:1]
	v_pk_mov_b32 v[50:51], v[0:1], v[0:1]
	v_pk_mov_b32 v[52:53], v[0:1], v[0:1]
	v_pk_mov_b32 v[54:55], v[0:1], v[0:1]
	v_pk_mov_b32 v[8:9], v[0:1], v[0:1]
	v_pk_mov_b32 v[10:11], v[0:1], v[0:1]
	v_pk_mov_b32 v[12:13], v[0:1], v[0:1]
	v_pk_mov_b32 v[14:15], v[0:1], v[0:1]
	v_pk_mov_b32 v[24:25], v[0:1], v[0:1]
	v_pk_mov_b32 v[26:27], v[0:1], v[0:1]
	v_pk_mov_b32 v[28:29], v[0:1], v[0:1]
	v_pk_mov_b32 v[30:31], v[0:1], v[0:1]
	v_pk_mov_b32 v[40:41], v[0:1], v[0:1]
	v_pk_mov_b32 v[42:43], v[0:1], v[0:1]
	v_pk_mov_b32 v[44:45], v[0:1], v[0:1]
	v_pk_mov_b32 v[46:47], v[0:1], v[0:1]
	v_pk_mov_b32 v[56:57], v[0:1], v[0:1]
	v_pk_mov_b32 v[58:59], v[0:1], v[0:1]
	v_pk_mov_b32 v[60:61], v[0:1], v[0:1]
	v_pk_mov_b32 v[62:63], v[0:1], v[0:1]
	v_pk_mov_b32 v[64:65], v[0:1], v[0:1]
	v_pk_mov_b32 v[66:67], v[0:1], v[0:1]
	v_pk_mov_b32 v[68:69], v[0:1], v[0:1]
	v_pk_mov_b32 v[70:71], v[0:1], v[0:1]
	v_pk_mov_b32 v[80:81], v[0:1], v[0:1]
	v_pk_mov_b32 v[82:83], v[0:1], v[0:1]
	v_pk_mov_b32 v[84:85], v[0:1], v[0:1]
	v_pk_mov_b32 v[86:87], v[0:1], v[0:1]
	v_pk_mov_b32 v[96:97], v[0:1], v[0:1]
	v_pk_mov_b32 v[98:99], v[0:1], v[0:1]
	v_pk_mov_b32 v[100:101], v[0:1], v[0:1]
	v_pk_mov_b32 v[102:103], v[0:1], v[0:1]
	v_pk_mov_b32 v[112:113], v[0:1], v[0:1]
	v_pk_mov_b32 v[114:115], v[0:1], v[0:1]
	v_pk_mov_b32 v[116:117], v[0:1], v[0:1]
	v_pk_mov_b32 v[118:119], v[0:1], v[0:1]
	v_pk_mov_b32 v[72:73], v[0:1], v[0:1]
	v_pk_mov_b32 v[74:75], v[0:1], v[0:1]
	v_pk_mov_b32 v[76:77], v[0:1], v[0:1]
	v_pk_mov_b32 v[78:79], v[0:1], v[0:1]
	v_pk_mov_b32 v[88:89], v[0:1], v[0:1]
	v_pk_mov_b32 v[90:91], v[0:1], v[0:1]
	v_pk_mov_b32 v[92:93], v[0:1], v[0:1]
	v_pk_mov_b32 v[94:95], v[0:1], v[0:1]
	v_pk_mov_b32 v[104:105], v[0:1], v[0:1]
	v_pk_mov_b32 v[106:107], v[0:1], v[0:1]
	v_pk_mov_b32 v[108:109], v[0:1], v[0:1]
	v_pk_mov_b32 v[110:111], v[0:1], v[0:1]
	v_pk_mov_b32 v[120:121], v[0:1], v[0:1]
	v_pk_mov_b32 v[122:123], v[0:1], v[0:1]
	v_pk_mov_b32 v[124:125], v[0:1], v[0:1]
	v_pk_mov_b32 v[126:127], v[0:1], v[0:1]

; template <class Epi, class Sched, bool ALIGN_EPI = false, bool SP2 = false>
; __device__ __forceinline__ void gemm_phase(PG8_LAS unsigned char* lds, const Gemm g, const Sched& S, const Epi& E) {
;     ...
;         const bool has_next = S.next(ui + 1, nxt);
;         const char* nA = has_next ? (const char*)g.A + (size_t)nxt.pm * tstep : cA; const char* nB = has_next ? (const char*)g.Bt + (size_t)nxt.pn * tstep : cB;
;     ...
; #pragma unroll
;         for (int a = 0; a < 2; ++a)
; #pragma unroll
;             for (int b = 0; b < 2; ++b)
; #pragma unroll
;                 for (int m = 0; m < 4; ++m)
; #pragma unroll
;                     for (int n = 0; n < 2; ++n) acc[a][b][m][n] = (f32x4){0.f, 0.f, 0.f, 0.f};
.LBB0_622:
	s_ashr_i32 s17, s16, 31
	s_lshl_b64 s[18:19], s[16:17], 18
	s_add_u32 s18, s31, s18
	s_addc_u32 s19, s33, s19
	s_and_b64 s[20:21], s[4:5], exec
	s_cselect_b32 s17, s19, s25
	s_cselect_b32 s51, s18, s24
	s_ashr_i32 s15, s14, 31
	s_lshl_b64 s[20:21], s[14:15], 18
	s_add_u32 s20, s34, s20
	s_addc_u32 s21, s35, s21
	s_and_b64 s[28:29], s[4:5], exec
	s_cselect_b32 s15, s21, s27
	s_cselect_b32 s52, s20, s26
	s_add_u32 s24, s24, 0x20080
	s_addc_u32 s25, s25, 0
	s_add_u32 s53, s26, 0x100
	v_mov_b32_e32 v0, 0
	s_addc_u32 s54, s27, 0
	s_mov_b32 s55, -2
	v_mov_b32_e32 v1, v0
	v_pk_mov_b32 v[2:3], v[0:1], v[0:1]
	v_pk_mov_b32 v[4:5], v[0:1], v[0:1]
	v_pk_mov_b32 v[6:7], v[0:1], v[0:1]
	v_pk_mov_b32 v[16:17], v[0:1], v[0:1]
	v_pk_mov_b32 v[18:19], v[0:1], v[0:1]
	v_pk_mov_b32 v[20:21], v[0:1], v[0:1]
	v_pk_mov_b32 v[22:23], v[0:1], v[0:1]
	v_pk_mov_b32 v[32:33], v[0:1], v[0:1]
	v_pk_mov_b32 v[34:35], v[0:1], v[0:1]
	v_pk_mov_b32 v[36:37], v[0:1], v[0:1]
	v_pk_mov_b32 v[38:39], v[0:1], v[0:1]
	v_pk_mov_b32 v[48:49], v[0:1], v[0:1]
	v_pk_mov_b32 v[50:51], v[0:1], v[0:1]
	v_pk_mov_b32 v[52:53], v[0:1], v[0:1]
	v_pk_mov_b32 v[54:55], v[0:1], v[0:1]
	v_pk_mov_b32 v[8:9], v[0:1], v[0:1]
	v_pk_mov_b32 v[10:11], v[0:1], v[0:1]
	v_pk_mov_b32 v[12:13], v[0:1], v[0:1]
	v_pk_mov_b32 v[14:15], v[0:1], v[0:1]
	v_pk_mov_b32 v[24:25], v[0:1], v[0:1]
	v_pk_mov_b32 v[26:27], v[0:1], v[0:1]
	v_pk_mov_b32 v[28:29], v[0:1], v[0:1]
	v_pk_mov_b32 v[30:31], v[0:1], v[0:1]
	v_pk_mov_b32 v[40:41], v[0:1], v[0:1]
	v_pk_mov_b32 v[42:43], v[0:1], v[0:1]
	v_pk_mov_b32 v[44:45], v[0:1], v[0:1]
	v_pk_mov_b32 v[46:47], v[0:1], v[0:1]
	v_pk_mov_b32 v[56:57], v[0:1], v[0:1]
	v_pk_mov_b32 v[58:59], v[0:1], v[0:1]
	v_pk_mov_b32 v[60:61], v[0:1], v[0:1]
	v_pk_mov_b32 v[62:63], v[0:1], v[0:1]
	v_pk_mov_b32 v[64:65], v[0:1], v[0:1]
	v_pk_mov_b32 v[66:67], v[0:1], v[0:1]
	v_pk_mov_b32 v[68:69], v[0:1], v[0:1]
	v_pk_mov_b32 v[70:71], v[0:1], v[0:1]
	v_pk_mov_b32 v[80:81], v[0:1], v[0:1]
	v_pk_mov_b32 v[82:83], v[0:1], v[0:1]
	v_pk_mov_b32 v[84:85], v[0:1], v[0:1]
	v_pk_mov_b32 v[86:87], v[0:1], v[0:1]
	v_pk_mov_b32 v[96:97], v[0:1], v[0:1]
	v_pk_mov_b32 v[98:99], v[0:1], v[0:1]
	v_pk_mov_b32 v[100:101], v[0:1], v[0:1]
	v_pk_mov_b32 v[102:103], v[0:1], v[0:1]
	v_pk_mov_b32 v[112:113], v[0:1], v[0:1]
	v_pk_mov_b32 v[114:115], v[0:1], v[0:1]
	v_pk_mov_b32 v[116:117], v[0:1], v[0:1]
	v_pk_mov_b32 v[118:119], v[0:1], v[0:1]
	v_pk_mov_b32 v[72:73], v[0:1], v[0:1]
	v_pk_mov_b32 v[74:75], v[0:1], v[0:1]
	v_pk_mov_b32 v[76:77], v[0:1], v[0:1]
	v_pk_mov_b32 v[78:79], v[0:1], v[0:1]
	v_pk_mov_b32 v[88:89], v[0:1], v[0:1]
	v_pk_mov_b32 v[90:91], v[0:1], v[0:1]
	v_pk_mov_b32 v[92:93], v[0:1], v[0:1]
	v_pk_mov_b32 v[94:95], v[0:1], v[0:1]
	v_pk_mov_b32 v[104:105], v[0:1], v[0:1]
	v_pk_mov_b32 v[106:107], v[0:1], v[0:1]
	v_pk_mov_b32 v[108:109], v[0:1], v[0:1]
	v_pk_mov_b32 v[110:111], v[0:1], v[0:1]
	v_pk_mov_b32 v[120:121], v[0:1], v[0:1]
	v_pk_mov_b32 v[122:123], v[0:1], v[0:1]
	v_pk_mov_b32 v[124:125], v[0:1], v[0:1]
	v_pk_mov_b32 v[126:127], v[0:1], v[0:1]

; template <class Epi, class Sched, bool ALIGN_EPI = false, bool SP2 = false>
; __device__ __forceinline__ void gemm_phase(PG8_LAS unsigned char* lds, const Gemm g, const Sched& S, const Epi& E) {
;     ...
;         const bool has_next = S.next(ui + 1, nxt);
;         const char* nA = has_next ? (const char*)g.A + (size_t)nxt.pm * tstep : cA; const char* nB = has_next ? (const char*)g.Bt + (size_t)nxt.pn * tstep : cB;
;     ...
; #pragma unroll
;         for (int a = 0; a < 2; ++a)
; #pragma unroll
;             for (int b = 0; b < 2; ++b)
; #pragma unroll
;                 for (int m = 0; m < 4; ++m)
; #pragma unroll
;                     for (int n = 0; n < 2; ++n) acc[a][b][m][n] = (f32x4){0.f, 0.f, 0.f, 0.f};
.LBB0_1048:
	s_ashr_i32 s21, s20, 31
	s_lshl_b64 s[22:23], s[20:21], 19
	s_add_u32 s22, s36, s22
	s_addc_u32 s23, s37, s23
	s_and_b64 s[24:25], s[6:7], exec
	s_cselect_b32 s21, s23, s29
	s_cselect_b32 s50, s22, s28
	s_ashr_i32 s19, s18, 31
	s_lshl_b64 s[24:25], s[18:19], 19
	s_add_u32 s24, s38, s24
	s_addc_u32 s25, s39, s25
	s_and_b64 s[34:35], s[6:7], exec
	s_cselect_b32 s19, s25, s31
	s_cselect_b32 s51, s24, s30
	s_add_u32 s28, s28, 0x40080
	s_addc_u32 s29, s29, 0
	s_add_u32 s52, s30, 0x100
	v_mov_b32_e32 v0, 0
	s_addc_u32 s53, s31, 0
	s_mov_b32 s54, -2
	v_mov_b32_e32 v1, v0
	v_pk_mov_b32 v[2:3], v[0:1], v[0:1]
	v_pk_mov_b32 v[4:5], v[0:1], v[0:1]
	v_pk_mov_b32 v[6:7], v[0:1], v[0:1]
	v_pk_mov_b32 v[16:17], v[0:1], v[0:1]
	v_pk_mov_b32 v[18:19], v[0:1], v[0:1]
	v_pk_mov_b32 v[20:21], v[0:1], v[0:1]
	v_pk_mov_b32 v[22:23], v[0:1], v[0:1]
	v_pk_mov_b32 v[32:33], v[0:1], v[0:1]
	v_pk_mov_b32 v[34:35], v[0:1], v[0:1]
	v_pk_mov_b32 v[36:37], v[0:1], v[0:1]
	v_pk_mov_b32 v[38:39], v[0:1], v[0:1]
	v_pk_mov_b32 v[48:49], v[0:1], v[0:1]
	v_pk_mov_b32 v[50:51], v[0:1], v[0:1]
	v_pk_mov_b32 v[52:53], v[0:1], v[0:1]
	v_pk_mov_b32 v[54:55], v[0:1], v[0:1]
	v_pk_mov_b32 v[8:9], v[0:1], v[0:1]
	v_pk_mov_b32 v[10:11], v[0:1], v[0:1]
	v_pk_mov_b32 v[12:13], v[0:1], v[0:1]
	v_pk_mov_b32 v[14:15], v[0:1], v[0:1]
	v_pk_mov_b32 v[24:25], v[0:1], v[0:1]
	v_pk_mov_b32 v[26:27], v[0:1], v[0:1]
	v_pk_mov_b32 v[28:29], v[0:1], v[0:1]
	v_pk_mov_b32 v[30:31], v[0:1], v[0:1]
	v_pk_mov_b32 v[40:41], v[0:1], v[0:1]
	v_pk_mov_b32 v[42:43], v[0:1], v[0:1]
	v_pk_mov_b32 v[44:45], v[0:1], v[0:1]
	v_pk_mov_b32 v[46:47], v[0:1], v[0:1]
	v_pk_mov_b32 v[56:57], v[0:1], v[0:1]
	v_pk_mov_b32 v[58:59], v[0:1], v[0:1]
	v_pk_mov_b32 v[60:61], v[0:1], v[0:1]
	v_pk_mov_b32 v[62:63], v[0:1], v[0:1]
	v_pk_mov_b32 v[64:65], v[0:1], v[0:1]
	v_pk_mov_b32 v[66:67], v[0:1], v[0:1]
	v_pk_mov_b32 v[68:69], v[0:1], v[0:1]
	v_pk_mov_b32 v[70:71], v[0:1], v[0:1]
	v_pk_mov_b32 v[80:81], v[0:1], v[0:1]
	v_pk_mov_b32 v[82:83], v[0:1], v[0:1]
	v_pk_mov_b32 v[84:85], v[0:1], v[0:1]
	v_pk_mov_b32 v[86:87], v[0:1], v[0:1]
	v_pk_mov_b32 v[96:97], v[0:1], v[0:1]
	v_pk_mov_b32 v[98:99], v[0:1], v[0:1]
	v_pk_mov_b32 v[100:101], v[0:1], v[0:1]
	v_pk_mov_b32 v[102:103], v[0:1], v[0:1]
	v_pk_mov_b32 v[112:113], v[0:1], v[0:1]
	v_pk_mov_b32 v[114:115], v[0:1], v[0:1]
	v_pk_mov_b32 v[116:117], v[0:1], v[0:1]
	v_pk_mov_b32 v[118:119], v[0:1], v[0:1]
	v_pk_mov_b32 v[72:73], v[0:1], v[0:1]
	v_pk_mov_b32 v[74:75], v[0:1], v[0:1]
	v_pk_mov_b32 v[76:77], v[0:1], v[0:1]
	v_pk_mov_b32 v[78:79], v[0:1], v[0:1]
	v_pk_mov_b32 v[88:89], v[0:1], v[0:1]
	v_pk_mov_b32 v[90:91], v[0:1], v[0:1]
	v_pk_mov_b32 v[92:93], v[0:1], v[0:1]
	v_pk_mov_b32 v[94:95], v[0:1], v[0:1]
	v_pk_mov_b32 v[104:105], v[0:1], v[0:1]
	v_pk_mov_b32 v[106:107], v[0:1], v[0:1]
	v_pk_mov_b32 v[108:109], v[0:1], v[0:1]
	v_pk_mov_b32 v[110:111], v[0:1], v[0:1]
	v_pk_mov_b32 v[120:121], v[0:1], v[0:1]
	v_pk_mov_b32 v[122:123], v[0:1], v[0:1]
	v_pk_mov_b32 v[124:125], v[0:1], v[0:1]
	v_pk_mov_b32 v[126:127], v[0:1], v[0:1]

; template <class Epi, class Sched, bool ALIGN_EPI = false, bool SP2 = false>
; __device__ __forceinline__ void gemm_phase(PG8_LAS unsigned char* lds, const Gemm g, const Sched& S, const Epi& E) {
;     ...
;         const bool has_next = S.next(ui + 1, nxt);
;         const char* nA = has_next ? (const char*)g.A + (size_t)nxt.pm * tstep : cA; const char* nB = has_next ? (const char*)g.Bt + (size_t)nxt.pn * tstep : cB;
;     ...
; #pragma unroll
;         for (int a = 0; a < 2; ++a)
; #pragma unroll
;             for (int b = 0; b < 2; ++b)
; #pragma unroll
;                 for (int m = 0; m < 4; ++m)
; #pragma unroll
;                     for (int n = 0; n < 2; ++n) acc[a][b][m][n] = (f32x4){0.f, 0.f, 0.f, 0.f};
.LBB0_1072:
	s_ashr_i32 s21, s20, 31
	s_lshl_b64 s[22:23], s[20:21], 19
	s_add_u32 s22, s36, s22
	s_addc_u32 s23, s37, s23
	s_and_b64 s[24:25], s[6:7], exec
	s_cselect_b32 s21, s23, s29
	s_cselect_b32 s33, s22, s28
	s_ashr_i32 s19, s18, 31
	s_lshl_b64 s[24:25], s[18:19], 19
	s_add_u32 s24, s38, s24
	s_addc_u32 s25, s39, s25
	s_and_b64 s[34:35], s[6:7], exec
	s_cselect_b32 s19, s25, s31
	s_cselect_b32 s51, s24, s30
	s_add_u32 s28, s28, 0x40080
	s_addc_u32 s29, s29, 0
	s_add_u32 s52, s30, 0x100
	v_mov_b32_e32 v0, 0
	s_addc_u32 s53, s31, 0
	s_mov_b32 s54, -2
	v_mov_b32_e32 v1, v0
	v_pk_mov_b32 v[2:3], v[0:1], v[0:1]
	v_pk_mov_b32 v[4:5], v[0:1], v[0:1]
	v_pk_mov_b32 v[6:7], v[0:1], v[0:1]
	v_pk_mov_b32 v[16:17], v[0:1], v[0:1]
	v_pk_mov_b32 v[18:19], v[0:1], v[0:1]
	v_pk_mov_b32 v[20:21], v[0:1], v[0:1]
	v_pk_mov_b32 v[22:23], v[0:1], v[0:1]
	v_pk_mov_b32 v[32:33], v[0:1], v[0:1]
	v_pk_mov_b32 v[34:35], v[0:1], v[0:1]
	v_pk_mov_b32 v[36:37], v[0:1], v[0:1]
	v_pk_mov_b32 v[38:39], v[0:1], v[0:1]
	v_pk_mov_b32 v[48:49], v[0:1], v[0:1]
	v_pk_mov_b32 v[50:51], v[0:1], v[0:1]
	v_pk_mov_b32 v[52:53], v[0:1], v[0:1]
	v_pk_mov_b32 v[54:55], v[0:1], v[0:1]
	v_pk_mov_b32 v[8:9], v[0:1], v[0:1]
	v_pk_mov_b32 v[10:11], v[0:1], v[0:1]
	v_pk_mov_b32 v[12:13], v[0:1], v[0:1]
	v_pk_mov_b32 v[14:15], v[0:1], v[0:1]
	v_pk_mov_b32 v[24:25], v[0:1], v[0:1]
	v_pk_mov_b32 v[26:27], v[0:1], v[0:1]
	v_pk_mov_b32 v[28:29], v[0:1], v[0:1]
	v_pk_mov_b32 v[30:31], v[0:1], v[0:1]
	v_pk_mov_b32 v[40:41], v[0:1], v[0:1]
	v_pk_mov_b32 v[42:43], v[0:1], v[0:1]
	v_pk_mov_b32 v[44:45], v[0:1], v[0:1]
	v_pk_mov_b32 v[46:47], v[0:1], v[0:1]
	v_pk_mov_b32 v[56:57], v[0:1], v[0:1]
	v_pk_mov_b32 v[58:59], v[0:1], v[0:1]
	v_pk_mov_b32 v[60:61], v[0:1], v[0:1]
	v_pk_mov_b32 v[62:63], v[0:1], v[0:1]
	v_pk_mov_b32 v[64:65], v[0:1], v[0:1]
	v_pk_mov_b32 v[66:67], v[0:1], v[0:1]
	v_pk_mov_b32 v[68:69], v[0:1], v[0:1]
	v_pk_mov_b32 v[70:71], v[0:1], v[0:1]
	v_pk_mov_b32 v[80:81], v[0:1], v[0:1]
	v_pk_mov_b32 v[82:83], v[0:1], v[0:1]
	v_pk_mov_b32 v[84:85], v[0:1], v[0:1]
	v_pk_mov_b32 v[86:87], v[0:1], v[0:1]
	v_pk_mov_b32 v[96:97], v[0:1], v[0:1]
	v_pk_mov_b32 v[98:99], v[0:1], v[0:1]
	v_pk_mov_b32 v[100:101], v[0:1], v[0:1]
	v_pk_mov_b32 v[102:103], v[0:1], v[0:1]
	v_pk_mov_b32 v[112:113], v[0:1], v[0:1]
	v_pk_mov_b32 v[114:115], v[0:1], v[0:1]
	v_pk_mov_b32 v[116:117], v[0:1], v[0:1]
	v_pk_mov_b32 v[118:119], v[0:1], v[0:1]
	v_pk_mov_b32 v[72:73], v[0:1], v[0:1]
	v_pk_mov_b32 v[74:75], v[0:1], v[0:1]
	v_pk_mov_b32 v[76:77], v[0:1], v[0:1]
	v_pk_mov_b32 v[78:79], v[0:1], v[0:1]
	v_pk_mov_b32 v[88:89], v[0:1], v[0:1]
	v_pk_mov_b32 v[90:91], v[0:1], v[0:1]
	v_pk_mov_b32 v[92:93], v[0:1], v[0:1]
	v_pk_mov_b32 v[94:95], v[0:1], v[0:1]
	v_pk_mov_b32 v[104:105], v[0:1], v[0:1]
	v_pk_mov_b32 v[106:107], v[0:1], v[0:1]
	v_pk_mov_b32 v[108:109], v[0:1], v[0:1]
	v_pk_mov_b32 v[110:111], v[0:1], v[0:1]
	v_pk_mov_b32 v[120:121], v[0:1], v[0:1]
	v_pk_mov_b32 v[122:123], v[0:1], v[0:1]
	v_pk_mov_b32 v[124:125], v[0:1], v[0:1]
	v_pk_mov_b32 v[126:127], v[0:1], v[0:1]

; template <class Epi, class Sched, bool ALIGN_EPI = false, bool SP2 = false>
; __device__ __forceinline__ void gemm_phase(PG8_LAS unsigned char* lds, const Gemm g, const Sched& S, const Epi& E) {
;     ...
;         const bool has_next = S.next(ui + 1, nxt);
;         const char* nA = has_next ? (const char*)g.A + (size_t)nxt.pm * tstep : cA; const char* nB = has_next ? (const char*)g.Bt + (size_t)nxt.pn * tstep : cB;
;     ...
; #pragma unroll
;         for (int a = 0; a < 2; ++a)
; #pragma unroll
;             for (int b = 0; b < 2; ++b)
; #pragma unroll
;                 for (int m = 0; m < 4; ++m)
; #pragma unroll
;                     for (int n = 0; n < 2; ++n) acc[a][b][m][n] = (f32x4){0.f, 0.f, 0.f, 0.f};
.LBB0_1150:
	s_ashr_i32 s23, s22, 31
	s_lshl_b64 s[24:25], s[22:23], 20
	s_add_u32 s24, s2, s24
	s_addc_u32 s25, s33, s25
	s_and_b64 s[26:27], s[8:9], exec
	s_cselect_b32 s23, s25, s35
	s_cselect_b32 s29, s24, s34
	s_ashr_i32 s21, s20, 31
	s_lshl_b64 s[26:27], s[20:21], 20
	s_add_u32 s26, s40, s26
	s_addc_u32 s27, s41, s27
	s_and_b64 s[38:39], s[8:9], exec
	s_cselect_b32 s21, s27, s37
	s_cselect_b32 s31, s26, s36
	s_add_u32 s34, s34, 0x80080
	s_addc_u32 s35, s35, 0
	s_add_u32 s54, s36, 0x100
	v_mov_b32_e32 v0, 0
	s_addc_u32 s55, s37, 0
	s_mov_b32 s56, -2
	v_mov_b32_e32 v1, v0
	v_pk_mov_b32 v[2:3], v[0:1], v[0:1]
	v_mov_b32_e32 v4, v0
	s_waitcnt lgkmcnt(0)
	v_mov_b32_e32 v5, v0
	v_pk_mov_b32 v[6:7], v[0:1], v[0:1]
	v_pk_mov_b32 v[16:17], v[0:1], v[0:1]
	v_pk_mov_b32 v[18:19], v[0:1], v[0:1]
	v_pk_mov_b32 v[20:21], v[0:1], v[0:1]
	v_pk_mov_b32 v[22:23], v[0:1], v[0:1]
	v_pk_mov_b32 v[32:33], v[0:1], v[0:1]
	v_pk_mov_b32 v[34:35], v[0:1], v[0:1]
	v_pk_mov_b32 v[36:37], v[0:1], v[0:1]
	v_pk_mov_b32 v[38:39], v[0:1], v[0:1]
	v_pk_mov_b32 v[48:49], v[0:1], v[0:1]
	v_pk_mov_b32 v[50:51], v[0:1], v[0:1]
	v_pk_mov_b32 v[52:53], v[0:1], v[0:1]
	v_pk_mov_b32 v[54:55], v[0:1], v[0:1]
	v_pk_mov_b32 v[8:9], v[0:1], v[0:1]
	v_pk_mov_b32 v[10:11], v[0:1], v[0:1]
	v_pk_mov_b32 v[12:13], v[0:1], v[0:1]
	v_pk_mov_b32 v[14:15], v[0:1], v[0:1]
	v_pk_mov_b32 v[24:25], v[0:1], v[0:1]
	v_pk_mov_b32 v[26:27], v[0:1], v[0:1]
	v_pk_mov_b32 v[28:29], v[0:1], v[0:1]
	v_pk_mov_b32 v[30:31], v[0:1], v[0:1]
	v_pk_mov_b32 v[40:41], v[0:1], v[0:1]
	v_pk_mov_b32 v[42:43], v[0:1], v[0:1]
	v_pk_mov_b32 v[44:45], v[0:1], v[0:1]
	v_pk_mov_b32 v[46:47], v[0:1], v[0:1]
	v_pk_mov_b32 v[56:57], v[0:1], v[0:1]
	v_pk_mov_b32 v[58:59], v[0:1], v[0:1]
	v_pk_mov_b32 v[60:61], v[0:1], v[0:1]
	v_pk_mov_b32 v[62:63], v[0:1], v[0:1]
	v_pk_mov_b32 v[64:65], v[0:1], v[0:1]
	v_pk_mov_b32 v[66:67], v[0:1], v[0:1]
	v_pk_mov_b32 v[68:69], v[0:1], v[0:1]
	v_pk_mov_b32 v[70:71], v[0:1], v[0:1]
	v_pk_mov_b32 v[80:81], v[0:1], v[0:1]
	v_pk_mov_b32 v[82:83], v[0:1], v[0:1]
	v_pk_mov_b32 v[84:85], v[0:1], v[0:1]
	v_pk_mov_b32 v[86:87], v[0:1], v[0:1]
	v_pk_mov_b32 v[96:97], v[0:1], v[0:1]
	v_pk_mov_b32 v[98:99], v[0:1], v[0:1]
	v_pk_mov_b32 v[100:101], v[0:1], v[0:1]
	v_pk_mov_b32 v[102:103], v[0:1], v[0:1]
	v_pk_mov_b32 v[112:113], v[0:1], v[0:1]
	v_pk_mov_b32 v[114:115], v[0:1], v[0:1]
	v_pk_mov_b32 v[116:117], v[0:1], v[0:1]
	v_pk_mov_b32 v[118:119], v[0:1], v[0:1]
	v_pk_mov_b32 v[72:73], v[0:1], v[0:1]
	v_pk_mov_b32 v[74:75], v[0:1], v[0:1]
	v_pk_mov_b32 v[76:77], v[0:1], v[0:1]
	v_pk_mov_b32 v[78:79], v[0:1], v[0:1]
	v_pk_mov_b32 v[88:89], v[0:1], v[0:1]
	v_pk_mov_b32 v[90:91], v[0:1], v[0:1]
	v_pk_mov_b32 v[92:93], v[0:1], v[0:1]
	v_pk_mov_b32 v[94:95], v[0:1], v[0:1]
	v_pk_mov_b32 v[104:105], v[0:1], v[0:1]
	v_pk_mov_b32 v[106:107], v[0:1], v[0:1]
	v_pk_mov_b32 v[108:109], v[0:1], v[0:1]
	v_pk_mov_b32 v[110:111], v[0:1], v[0:1]
	v_pk_mov_b32 v[120:121], v[0:1], v[0:1]
	v_pk_mov_b32 v[122:123], v[0:1], v[0:1]
	v_pk_mov_b32 v[124:125], v[0:1], v[0:1]
	v_pk_mov_b32 v[126:127], v[0:1], v[0:1]

; template <class Epi, class Sched, bool ALIGN_EPI = false, bool SP2 = false>
; __device__ __forceinline__ void gemm_phase(PG8_LAS unsigned char* lds, const Gemm g, const Sched& S, const Epi& E) {
;     ...
;         const bool has_next = S.next(ui + 1, nxt);
;         const char* nA = has_next ? (const char*)g.A + (size_t)nxt.pm * tstep : cA; const char* nB = has_next ? (const char*)g.Bt + (size_t)nxt.pn * tstep : cB;
;     ...
; #pragma unroll
;         for (int a = 0; a < 2; ++a)
; #pragma unroll
;             for (int b = 0; b < 2; ++b)
; #pragma unroll
;                 for (int m = 0; m < 4; ++m)
; #pragma unroll
;                     for (int n = 0; n < 2; ++n) acc[a][b][m][n] = (f32x4){0.f, 0.f, 0.f, 0.f};
.LBB0_1293:
	s_ashr_i32 s21, s20, 31
	s_lshl_b64 s[22:23], s[20:21], 20
	s_add_u32 s22, s33, s22
	s_addc_u32 s23, s36, s23
	s_and_b64 s[24:25], s[8:9], exec
	s_cselect_b32 s21, s23, s29
	s_cselect_b32 s49, s22, s28
	s_ashr_i32 s19, s18, 31
	s_lshl_b64 s[24:25], s[18:19], 20
	s_add_u32 s24, s37, s24
	s_addc_u32 s25, s38, s25
	s_and_b64 s[34:35], s[8:9], exec
	s_cselect_b32 s19, s25, s31
	s_cselect_b32 s50, s24, s30
	s_add_u32 s28, s28, 0x80080
	s_addc_u32 s29, s29, 0
	s_add_u32 s51, s30, 0x100
	v_mov_b32_e32 v0, 0
	s_addc_u32 s52, s31, 0
	s_mov_b32 s53, -2
	v_mov_b32_e32 v1, v0
	v_pk_mov_b32 v[2:3], v[0:1], v[0:1]
	v_pk_mov_b32 v[4:5], v[0:1], v[0:1]
	v_pk_mov_b32 v[6:7], v[0:1], v[0:1]
	v_pk_mov_b32 v[12:13], v[0:1], v[0:1]
	v_pk_mov_b32 v[14:15], v[0:1], v[0:1]
	v_pk_mov_b32 v[20:21], v[0:1], v[0:1]
	v_pk_mov_b32 v[22:23], v[0:1], v[0:1]
	v_pk_mov_b32 v[28:29], v[0:1], v[0:1]
	v_pk_mov_b32 v[30:31], v[0:1], v[0:1]
	v_pk_mov_b32 v[36:37], v[0:1], v[0:1]
	v_pk_mov_b32 v[38:39], v[0:1], v[0:1]
	v_pk_mov_b32 v[44:45], v[0:1], v[0:1]
	v_pk_mov_b32 v[46:47], v[0:1], v[0:1]
	v_pk_mov_b32 v[52:53], v[0:1], v[0:1]
	v_pk_mov_b32 v[54:55], v[0:1], v[0:1]
	v_pk_mov_b32 v[8:9], v[0:1], v[0:1]
	v_pk_mov_b32 v[10:11], v[0:1], v[0:1]
	v_pk_mov_b32 v[16:17], v[0:1], v[0:1]
	v_pk_mov_b32 v[18:19], v[0:1], v[0:1]
	v_pk_mov_b32 v[24:25], v[0:1], v[0:1]
	v_pk_mov_b32 v[26:27], v[0:1], v[0:1]
	v_pk_mov_b32 v[32:33], v[0:1], v[0:1]
	v_pk_mov_b32 v[34:35], v[0:1], v[0:1]
	v_pk_mov_b32 v[40:41], v[0:1], v[0:1]
	v_pk_mov_b32 v[42:43], v[0:1], v[0:1]
	v_pk_mov_b32 v[48:49], v[0:1], v[0:1]
	v_pk_mov_b32 v[50:51], v[0:1], v[0:1]
	v_pk_mov_b32 v[56:57], v[0:1], v[0:1]
	v_pk_mov_b32 v[58:59], v[0:1], v[0:1]
	v_pk_mov_b32 v[60:61], v[0:1], v[0:1]
	v_pk_mov_b32 v[62:63], v[0:1], v[0:1]
	v_pk_mov_b32 v[64:65], v[0:1], v[0:1]
	v_pk_mov_b32 v[66:67], v[0:1], v[0:1]
	v_pk_mov_b32 v[68:69], v[0:1], v[0:1]
	v_pk_mov_b32 v[70:71], v[0:1], v[0:1]
	v_pk_mov_b32 v[76:77], v[0:1], v[0:1]
	v_pk_mov_b32 v[78:79], v[0:1], v[0:1]
	v_pk_mov_b32 v[84:85], v[0:1], v[0:1]
	v_pk_mov_b32 v[86:87], v[0:1], v[0:1]
	v_pk_mov_b32 v[92:93], v[0:1], v[0:1]
	v_pk_mov_b32 v[94:95], v[0:1], v[0:1]
	v_pk_mov_b32 v[100:101], v[0:1], v[0:1]
	v_pk_mov_b32 v[102:103], v[0:1], v[0:1]
	v_pk_mov_b32 v[108:109], v[0:1], v[0:1]
	v_pk_mov_b32 v[110:111], v[0:1], v[0:1]
	v_pk_mov_b32 v[116:117], v[0:1], v[0:1]
	v_pk_mov_b32 v[118:119], v[0:1], v[0:1]
	v_pk_mov_b32 v[72:73], v[0:1], v[0:1]
	v_pk_mov_b32 v[74:75], v[0:1], v[0:1]
	v_pk_mov_b32 v[80:81], v[0:1], v[0:1]
	v_pk_mov_b32 v[82:83], v[0:1], v[0:1]
	v_pk_mov_b32 v[88:89], v[0:1], v[0:1]
	v_pk_mov_b32 v[90:91], v[0:1], v[0:1]
	v_pk_mov_b32 v[96:97], v[0:1], v[0:1]
	v_pk_mov_b32 v[98:99], v[0:1], v[0:1]
	v_pk_mov_b32 v[104:105], v[0:1], v[0:1]
	v_pk_mov_b32 v[106:107], v[0:1], v[0:1]
	v_pk_mov_b32 v[112:113], v[0:1], v[0:1]
	v_pk_mov_b32 v[114:115], v[0:1], v[0:1]
	v_pk_mov_b32 v[120:121], v[0:1], v[0:1]
	v_pk_mov_b32 v[122:123], v[0:1], v[0:1]
	v_pk_mov_b32 v[124:125], v[0:1], v[0:1]
	v_pk_mov_b32 v[126:127], v[0:1], v[0:1]

; template <class Epi, class Sched, bool ALIGN_EPI = false, bool SP2 = false>
; __device__ __forceinline__ void gemm_phase(PG8_LAS unsigned char* lds, const Gemm g, const Sched& S, const Epi& E) {
;     ...
;         const bool has_next = S.next(ui + 1, nxt);
;         const char* nA = has_next ? (const char*)g.A + (size_t)nxt.pm * tstep : cA; const char* nB = has_next ? (const char*)g.Bt + (size_t)nxt.pn * tstep : cB;
;     ...
; #pragma unroll
;         for (int a = 0; a < 2; ++a)
; #pragma unroll
;             for (int b = 0; b < 2; ++b)
; #pragma unroll
;                 for (int m = 0; m < 4; ++m)
; #pragma unroll
;                     for (int n = 0; n < 2; ++n) acc[a][b][m][n] = (f32x4){0.f, 0.f, 0.f, 0.f};
.LBB0_1319:
	s_ashr_i32 s25, s24, 31
	s_lshl_b64 s[26:27], s[24:25], 17
	s_add_u32 s26, s33, s26
	s_addc_u32 s27, s55, s27
	s_and_b64 s[28:29], s[10:11], exec
	s_cselect_b32 s25, s27, s39
	s_cselect_b32 s31, s26, s38
	s_ashr_i32 s23, s22, 31
	s_lshl_b64 s[28:29], s[22:23], 17
	s_add_u32 s28, s56, s28
	s_addc_u32 s29, s57, s29
	s_and_b64 s[40:41], s[10:11], exec
	v_mov_b32_e32 v0, 0
	s_cselect_b32 s23, s29, s37
	s_cselect_b32 s35, s28, s36
	s_mov_b32 s44, 0
	s_mov_b64 s[40:41], -1
	s_mov_b64 s[42:43], 0
	v_mov_b32_e32 v1, v0
	v_pk_mov_b32 v[2:3], v[0:1], v[0:1]
	v_mov_b32_e32 v4, v0
	s_waitcnt lgkmcnt(0)
	v_mov_b32_e32 v5, v0
	v_pk_mov_b32 v[6:7], v[0:1], v[0:1]
	v_pk_mov_b32 v[16:17], v[0:1], v[0:1]
	v_pk_mov_b32 v[18:19], v[0:1], v[0:1]
	v_pk_mov_b32 v[20:21], v[0:1], v[0:1]
	v_pk_mov_b32 v[22:23], v[0:1], v[0:1]
	v_pk_mov_b32 v[32:33], v[0:1], v[0:1]
	v_pk_mov_b32 v[34:35], v[0:1], v[0:1]
	v_pk_mov_b32 v[36:37], v[0:1], v[0:1]
	v_pk_mov_b32 v[38:39], v[0:1], v[0:1]
	v_pk_mov_b32 v[48:49], v[0:1], v[0:1]
	v_pk_mov_b32 v[50:51], v[0:1], v[0:1]
	v_pk_mov_b32 v[52:53], v[0:1], v[0:1]
	v_pk_mov_b32 v[54:55], v[0:1], v[0:1]
	v_pk_mov_b32 v[8:9], v[0:1], v[0:1]
	v_pk_mov_b32 v[10:11], v[0:1], v[0:1]
	v_pk_mov_b32 v[12:13], v[0:1], v[0:1]
	v_pk_mov_b32 v[14:15], v[0:1], v[0:1]
	v_pk_mov_b32 v[24:25], v[0:1], v[0:1]
	v_pk_mov_b32 v[26:27], v[0:1], v[0:1]
	v_pk_mov_b32 v[28:29], v[0:1], v[0:1]
	v_pk_mov_b32 v[30:31], v[0:1], v[0:1]
	v_pk_mov_b32 v[40:41], v[0:1], v[0:1]
	v_pk_mov_b32 v[42:43], v[0:1], v[0:1]
	v_pk_mov_b32 v[44:45], v[0:1], v[0:1]
	v_pk_mov_b32 v[46:47], v[0:1], v[0:1]
	v_pk_mov_b32 v[56:57], v[0:1], v[0:1]
	v_pk_mov_b32 v[58:59], v[0:1], v[0:1]
	v_pk_mov_b32 v[60:61], v[0:1], v[0:1]
	v_pk_mov_b32 v[62:63], v[0:1], v[0:1]
	v_pk_mov_b32 v[64:65], v[0:1], v[0:1]
	v_pk_mov_b32 v[66:67], v[0:1], v[0:1]
	v_pk_mov_b32 v[68:69], v[0:1], v[0:1]
	v_pk_mov_b32 v[70:71], v[0:1], v[0:1]
	v_pk_mov_b32 v[80:81], v[0:1], v[0:1]
	v_pk_mov_b32 v[82:83], v[0:1], v[0:1]
	v_pk_mov_b32 v[84:85], v[0:1], v[0:1]
	v_pk_mov_b32 v[86:87], v[0:1], v[0:1]
	v_pk_mov_b32 v[96:97], v[0:1], v[0:1]
	v_pk_mov_b32 v[98:99], v[0:1], v[0:1]
	v_pk_mov_b32 v[100:101], v[0:1], v[0:1]
	v_pk_mov_b32 v[102:103], v[0:1], v[0:1]
	v_pk_mov_b32 v[112:113], v[0:1], v[0:1]
	v_pk_mov_b32 v[114:115], v[0:1], v[0:1]
	v_pk_mov_b32 v[116:117], v[0:1], v[0:1]
	v_pk_mov_b32 v[118:119], v[0:1], v[0:1]
	v_pk_mov_b32 v[72:73], v[0:1], v[0:1]
	v_pk_mov_b32 v[74:75], v[0:1], v[0:1]
	v_pk_mov_b32 v[76:77], v[0:1], v[0:1]
	v_pk_mov_b32 v[78:79], v[0:1], v[0:1]
	v_pk_mov_b32 v[88:89], v[0:1], v[0:1]
	v_pk_mov_b32 v[90:91], v[0:1], v[0:1]
	v_pk_mov_b32 v[92:93], v[0:1], v[0:1]
	v_pk_mov_b32 v[94:95], v[0:1], v[0:1]
	v_pk_mov_b32 v[104:105], v[0:1], v[0:1]
	v_pk_mov_b32 v[106:107], v[0:1], v[0:1]
	v_pk_mov_b32 v[108:109], v[0:1], v[0:1]
	v_pk_mov_b32 v[110:111], v[0:1], v[0:1]
	v_pk_mov_b32 v[120:121], v[0:1], v[0:1]
	v_pk_mov_b32 v[122:123], v[0:1], v[0:1]
	v_pk_mov_b32 v[124:125], v[0:1], v[0:1]
	v_pk_mov_b32 v[126:127], v[0:1], v[0:1]

; template <class Epi, class Sched, bool ALIGN_EPI = false, bool SP2 = false>
; __device__ __forceinline__ void gemm_phase(PG8_LAS unsigned char* lds, const Gemm g, const Sched& S, const Epi& E) {
;     ...
;         const bool has_next = S.next(ui + 1, nxt);
;         const char* nA = has_next ? (const char*)g.A + (size_t)nxt.pm * tstep : cA; const char* nB = has_next ? (const char*)g.Bt + (size_t)nxt.pn * tstep : cB;
;     ...
; #pragma unroll
;         for (int a = 0; a < 2; ++a)
; #pragma unroll
;             for (int b = 0; b < 2; ++b)
; #pragma unroll
;                 for (int m = 0; m < 4; ++m)
; #pragma unroll
;                     for (int n = 0; n < 2; ++n) acc[a][b][m][n] = (f32x4){0.f, 0.f, 0.f, 0.f};
.LBB0_1413:
	s_ashr_i32 s25, s24, 31
	s_lshl_b64 s[26:27], s[24:25], 22
	s_add_u32 s26, s33, s26
	s_addc_u32 s27, s42, s27
	s_and_b64 s[28:29], s[10:11], exec
	s_cselect_b32 s25, s27, s37
	s_cselect_b32 s31, s26, s36
	s_ashr_i32 s23, s22, 31
	s_lshl_b64 s[28:29], s[22:23], 22
	s_add_u32 s28, s43, s28
	s_addc_u32 s29, s44, s29
	s_and_b64 s[40:41], s[10:11], exec
	s_cselect_b32 s23, s29, s39
	s_cselect_b32 s35, s28, s38
	s_add_u32 s36, s36, 0x200080
	s_addc_u32 s37, s37, 0
	s_add_u32 s56, s38, 0x100
	v_mov_b32_e32 v0, 0
	s_addc_u32 s57, s39, 0
	s_mov_b32 s58, -2
	v_mov_b32_e32 v1, v0
	v_pk_mov_b32 v[2:3], v[0:1], v[0:1]
	v_mov_b32_e32 v4, v0
	s_waitcnt lgkmcnt(0)
	v_mov_b32_e32 v5, v0
	v_pk_mov_b32 v[6:7], v[0:1], v[0:1]
	v_pk_mov_b32 v[16:17], v[0:1], v[0:1]
	v_pk_mov_b32 v[18:19], v[0:1], v[0:1]
	v_pk_mov_b32 v[20:21], v[0:1], v[0:1]
	v_pk_mov_b32 v[22:23], v[0:1], v[0:1]
	v_pk_mov_b32 v[32:33], v[0:1], v[0:1]
	v_pk_mov_b32 v[34:35], v[0:1], v[0:1]
	v_pk_mov_b32 v[36:37], v[0:1], v[0:1]
	v_pk_mov_b32 v[38:39], v[0:1], v[0:1]
	v_pk_mov_b32 v[48:49], v[0:1], v[0:1]
	v_pk_mov_b32 v[50:51], v[0:1], v[0:1]
	v_pk_mov_b32 v[52:53], v[0:1], v[0:1]
	v_pk_mov_b32 v[54:55], v[0:1], v[0:1]
	v_pk_mov_b32 v[8:9], v[0:1], v[0:1]
	v_pk_mov_b32 v[10:11], v[0:1], v[0:1]
	v_pk_mov_b32 v[12:13], v[0:1], v[0:1]
	v_pk_mov_b32 v[14:15], v[0:1], v[0:1]
	v_pk_mov_b32 v[24:25], v[0:1], v[0:1]
	v_pk_mov_b32 v[26:27], v[0:1], v[0:1]
	v_pk_mov_b32 v[28:29], v[0:1], v[0:1]
	v_pk_mov_b32 v[30:31], v[0:1], v[0:1]
	v_pk_mov_b32 v[40:41], v[0:1], v[0:1]
	v_pk_mov_b32 v[42:43], v[0:1], v[0:1]
	v_pk_mov_b32 v[44:45], v[0:1], v[0:1]
	v_pk_mov_b32 v[46:47], v[0:1], v[0:1]
	v_pk_mov_b32 v[56:57], v[0:1], v[0:1]
	v_pk_mov_b32 v[58:59], v[0:1], v[0:1]
	v_pk_mov_b32 v[60:61], v[0:1], v[0:1]
	v_pk_mov_b32 v[62:63], v[0:1], v[0:1]
	v_pk_mov_b32 v[64:65], v[0:1], v[0:1]
	v_pk_mov_b32 v[66:67], v[0:1], v[0:1]
	v_pk_mov_b32 v[68:69], v[0:1], v[0:1]
	v_pk_mov_b32 v[70:71], v[0:1], v[0:1]
	v_pk_mov_b32 v[80:81], v[0:1], v[0:1]
	v_pk_mov_b32 v[82:83], v[0:1], v[0:1]
	v_pk_mov_b32 v[84:85], v[0:1], v[0:1]
	v_pk_mov_b32 v[86:87], v[0:1], v[0:1]
	v_pk_mov_b32 v[96:97], v[0:1], v[0:1]
	v_pk_mov_b32 v[98:99], v[0:1], v[0:1]
	v_pk_mov_b32 v[100:101], v[0:1], v[0:1]
	v_pk_mov_b32 v[102:103], v[0:1], v[0:1]
	v_pk_mov_b32 v[112:113], v[0:1], v[0:1]
	v_pk_mov_b32 v[114:115], v[0:1], v[0:1]
	v_pk_mov_b32 v[116:117], v[0:1], v[0:1]
	v_pk_mov_b32 v[118:119], v[0:1], v[0:1]
	v_pk_mov_b32 v[72:73], v[0:1], v[0:1]
	v_pk_mov_b32 v[74:75], v[0:1], v[0:1]
	v_pk_mov_b32 v[76:77], v[0:1], v[0:1]
	v_pk_mov_b32 v[78:79], v[0:1], v[0:1]
	v_pk_mov_b32 v[88:89], v[0:1], v[0:1]
	v_pk_mov_b32 v[90:91], v[0:1], v[0:1]
	v_pk_mov_b32 v[92:93], v[0:1], v[0:1]
	v_pk_mov_b32 v[94:95], v[0:1], v[0:1]
	v_pk_mov_b32 v[104:105], v[0:1], v[0:1]
	v_pk_mov_b32 v[106:107], v[0:1], v[0:1]
	v_pk_mov_b32 v[108:109], v[0:1], v[0:1]
	v_pk_mov_b32 v[110:111], v[0:1], v[0:1]
	v_pk_mov_b32 v[120:121], v[0:1], v[0:1]
	v_pk_mov_b32 v[122:123], v[0:1], v[0:1]
	v_pk_mov_b32 v[124:125], v[0:1], v[0:1]
	v_pk_mov_b32 v[126:127], v[0:1], v[0:1]

; template <class Epi, class Sched, bool ALIGN_EPI = false, bool SP2 = false>
; __device__ __forceinline__ void gemm_phase(PG8_LAS unsigned char* lds, const Gemm g, const Sched& S, const Epi& E) {
;     ...
;         const bool has_next = S.next(ui + 1, nxt);
;         const char* nA = has_next ? (const char*)g.A + (size_t)nxt.pm * tstep : cA; const char* nB = has_next ? (const char*)g.Bt + (size_t)nxt.pn * tstep : cB;
;     ...
; #pragma unroll
;         for (int a = 0; a < 2; ++a)
; #pragma unroll
;             for (int b = 0; b < 2; ++b)
; #pragma unroll
;                 for (int m = 0; m < 4; ++m)
; #pragma unroll
;                     for (int n = 0; n < 2; ++n) acc[a][b][m][n] = (f32x4){0.f, 0.f, 0.f, 0.f};
.LBB0_1561:
	s_ashr_i32 s21, s20, 31
	s_lshl_b64 s[22:23], s[20:21], 20
	s_add_u32 s22, s33, s22
	s_addc_u32 s23, s36, s23
	s_and_b64 s[24:25], s[0:1], exec
	s_cselect_b32 s21, s23, s29
	s_cselect_b32 s49, s22, s28
	s_ashr_i32 s19, s18, 31
	s_lshl_b64 s[24:25], s[18:19], 20
	s_add_u32 s24, s37, s24
	s_addc_u32 s25, s38, s25
	s_and_b64 s[34:35], s[0:1], exec
	s_cselect_b32 s19, s25, s31
	s_cselect_b32 s50, s24, s30
	s_add_u32 s28, s28, 0x80080
	s_addc_u32 s29, s29, 0
	s_add_u32 s51, s30, 0x100
	v_mov_b32_e32 v0, 0
	s_addc_u32 s52, s31, 0
	s_mov_b32 s53, -2
	v_mov_b32_e32 v1, v0
	v_pk_mov_b32 v[2:3], v[0:1], v[0:1]
	v_pk_mov_b32 v[4:5], v[0:1], v[0:1]
	v_pk_mov_b32 v[6:7], v[0:1], v[0:1]
	v_pk_mov_b32 v[16:17], v[0:1], v[0:1]
	v_pk_mov_b32 v[18:19], v[0:1], v[0:1]
	v_pk_mov_b32 v[20:21], v[0:1], v[0:1]
	v_pk_mov_b32 v[22:23], v[0:1], v[0:1]
	v_pk_mov_b32 v[32:33], v[0:1], v[0:1]
	v_pk_mov_b32 v[34:35], v[0:1], v[0:1]
	v_pk_mov_b32 v[36:37], v[0:1], v[0:1]
	v_pk_mov_b32 v[38:39], v[0:1], v[0:1]
	v_pk_mov_b32 v[48:49], v[0:1], v[0:1]
	v_pk_mov_b32 v[50:51], v[0:1], v[0:1]
	v_pk_mov_b32 v[52:53], v[0:1], v[0:1]
	v_pk_mov_b32 v[54:55], v[0:1], v[0:1]
	v_pk_mov_b32 v[8:9], v[0:1], v[0:1]
	v_pk_mov_b32 v[10:11], v[0:1], v[0:1]
	v_pk_mov_b32 v[12:13], v[0:1], v[0:1]
	v_pk_mov_b32 v[14:15], v[0:1], v[0:1]
	v_pk_mov_b32 v[24:25], v[0:1], v[0:1]
	v_pk_mov_b32 v[26:27], v[0:1], v[0:1]
	v_pk_mov_b32 v[28:29], v[0:1], v[0:1]
	v_pk_mov_b32 v[30:31], v[0:1], v[0:1]
	v_pk_mov_b32 v[40:41], v[0:1], v[0:1]
	v_pk_mov_b32 v[42:43], v[0:1], v[0:1]
	v_pk_mov_b32 v[44:45], v[0:1], v[0:1]
	v_pk_mov_b32 v[46:47], v[0:1], v[0:1]
	v_pk_mov_b32 v[56:57], v[0:1], v[0:1]
	v_pk_mov_b32 v[58:59], v[0:1], v[0:1]
	v_pk_mov_b32 v[60:61], v[0:1], v[0:1]
	v_pk_mov_b32 v[62:63], v[0:1], v[0:1]
	v_pk_mov_b32 v[64:65], v[0:1], v[0:1]
	v_pk_mov_b32 v[66:67], v[0:1], v[0:1]
	v_pk_mov_b32 v[68:69], v[0:1], v[0:1]
	v_pk_mov_b32 v[70:71], v[0:1], v[0:1]
	v_pk_mov_b32 v[80:81], v[0:1], v[0:1]
	v_pk_mov_b32 v[82:83], v[0:1], v[0:1]
	v_pk_mov_b32 v[84:85], v[0:1], v[0:1]
	v_pk_mov_b32 v[86:87], v[0:1], v[0:1]
	v_pk_mov_b32 v[96:97], v[0:1], v[0:1]
	v_pk_mov_b32 v[98:99], v[0:1], v[0:1]
	v_pk_mov_b32 v[100:101], v[0:1], v[0:1]
	v_pk_mov_b32 v[102:103], v[0:1], v[0:1]
	v_pk_mov_b32 v[112:113], v[0:1], v[0:1]
	v_pk_mov_b32 v[114:115], v[0:1], v[0:1]
	v_pk_mov_b32 v[116:117], v[0:1], v[0:1]
	v_pk_mov_b32 v[118:119], v[0:1], v[0:1]
	v_pk_mov_b32 v[72:73], v[0:1], v[0:1]
	v_pk_mov_b32 v[74:75], v[0:1], v[0:1]
	v_pk_mov_b32 v[76:77], v[0:1], v[0:1]
	v_pk_mov_b32 v[78:79], v[0:1], v[0:1]
	v_pk_mov_b32 v[88:89], v[0:1], v[0:1]
	v_pk_mov_b32 v[90:91], v[0:1], v[0:1]
	v_pk_mov_b32 v[92:93], v[0:1], v[0:1]
	v_pk_mov_b32 v[94:95], v[0:1], v[0:1]
	v_pk_mov_b32 v[104:105], v[0:1], v[0:1]
	v_pk_mov_b32 v[106:107], v[0:1], v[0:1]
	v_pk_mov_b32 v[108:109], v[0:1], v[0:1]
	v_pk_mov_b32 v[110:111], v[0:1], v[0:1]
	v_pk_mov_b32 v[120:121], v[0:1], v[0:1]
	v_pk_mov_b32 v[122:123], v[0:1], v[0:1]
	v_pk_mov_b32 v[124:125], v[0:1], v[0:1]
	v_pk_mov_b32 v[126:127], v[0:1], v[0:1]
